# attention early exit at carry < -17.4: every later weight is below 2^-25 and rounds to exactly 0 in the f16 weight conversion the baseline already applies (output unchanged)
# speedup vs baseline: 1.0168x; 1.0168x over previous
; #define LAS __attribute__((address_space(3)))
; __device__ __forceinline__ void scan_phase(const Ctx& F, const float* sbg) {
;     constexpr int T = 32, NCH = SEQ / T, STEPF = 448;
;     LAS float* bufs = (LAS float*)F.lds; LAS float* ybufs = (LAS float*)(F.lds + 2 * T * STEPF * 4);
;     const int lane = F.lane;
;     for (int unit = F.bid; unit < 256; unit += F.G) {
;         const int bh = unit >> 2, qtr = unit & 3;
;         float* Y = (float*)(F.ws + WS_Y) + (size_t)bh * SEQ * 64;
;         __syncthreads();
;         if (F.wave < 4) {
;             const int cgp = lane & 15, rl = F.wave * 4 + (lane >> 4), row = qtr * 16 + rl;
;             f32x2 s01 = {0.f, 0.f}, s23 = {0.f, 0.f};
;             const bool odd = (lane & 1) != 0;
;             const int lo_own = (odd ? 64 : 0) + 4 * cgp, lo_oth = (odd ? 0 : 64) + 4 * cgp;
;             const int yslot = cgp >> 1; bool ym[8];
; #pragma unroll
;             for (int e = 0; e < 8; ++e) ym[e] = odd && (yslot == e);
;             float ykeep = 0.f;
;             __syncthreads();
;             for (int ch = 0; ch < NCH; ++ch) {
;                 const LAS float* sb = bufs + (ch & 1) * (T * STEPF); LAS float* yb = ybufs + (ch & 1) * (T * 16) + rl;
.LBB0_658:
	s_cmp_lt_i32 s74, 7
	s_cselect_b64 s[0:1], -1, 0
	s_and_b64 s[0:1], s[0:1], s[2:3]
	v_writelane_b32 v253, s0, 42
	s_nop 1
	v_writelane_b32 v253, s1, 43
	s_xor_b64 s[0:1], s[0:1], -1
	s_cmpk_gt_i32 s80, 0xff
	s_cselect_b64 s[2:3], -1, 0
	s_or_b64 s[0:1], s[2:3], s[0:1]
	s_and_b64 vcc, exec, s[0:1]
	s_cbranch_vccnz .LBB0_703
	v_and_b32_e32 v4, 15, v163
	v_and_b32_e32 v2, 1, v163
	v_lshlrev_b32_e32 v1, 2, v4
	v_cmp_eq_u32_e64 s[2:3], 1, v2
	v_lshl_or_b32 v171, v2, 6, v1
	v_cmp_gt_u32_e32 vcc, 2, v4
	v_cndmask_b32_e64 v2, 64, 0, s[2:3]
	v_or_b32_e32 v173, v2, v1
	v_bfe_u32 v2, v163, 1, 3
	s_and_b64 s[4:5], s[2:3], vcc
	v_cmp_eq_u32_e32 vcc, 1, v2
	s_and_b64 s[6:7], s[2:3], vcc
	v_cmp_eq_u32_e32 vcc, 2, v2
	s_and_b64 s[8:9], s[2:3], vcc
	v_cmp_eq_u32_e32 vcc, 3, v2
	v_writelane_b32 v253, s87, 44
	s_and_b64 s[10:11], s[2:3], vcc
	v_cmp_eq_u32_e32 vcc, 4, v2
	v_writelane_b32 v253, s88, 45
	s_and_b64 s[12:13], s[2:3], vcc
	v_cmp_eq_u32_e32 vcc, 5, v2
	v_writelane_b32 v253, s89, 46
	s_and_b64 s[14:15], s[2:3], vcc
	v_cmp_eq_u32_e32 vcc, 6, v2
	v_writelane_b32 v253, s90, 47
	s_and_b64 s[16:17], s[2:3], vcc
	v_cmp_eq_u32_e32 vcc, 7, v2
	v_writelane_b32 v253, s91, 48
	s_and_b64 s[18:19], s[2:3], vcc
	v_writelane_b32 v253, s92, 49
	s_cmpk_gt_u32 s82, 0xff
	v_writelane_b32 v253, s93, 50
	s_cselect_b64 s[60:61], -1, 0
	s_lshl_b32 s0, s80, 2
	v_writelane_b32 v253, s94, 51
	s_add_i32 s0, s86, s0
	v_writelane_b32 v253, s95, 52
	s_add_u32 s1, s72, 0x1ac00000
	v_writelane_b32 v253, s1, 53
	s_addc_u32 s1, s73, 0
	v_writelane_b32 v253, s1, 54
	s_add_i32 s0, s0, -4
	v_add_u32_e32 v164, 0xffffff00, v163
	v_writelane_b32 v253, s0, 55
	s_add_u32 s0, s72, 0x1ec00000
	v_lshlrev_b32_e32 v198, 6, v2
	v_lshlrev_b32_e32 v2, 3, v163
	v_ashrrev_i32_e32 v165, 31, v164
	v_writelane_b32 v253, s0, 56
	s_addc_u32 s0, s73, 0
	v_lshl_add_u64 v[166:167], v[164:165], 4, s[66:67]
	v_ashrrev_i32_e32 v3, 3, v164
	v_and_b32_e32 v165, 56, v2
	s_add_u32 s68, s72, 0xec00000
	v_lshlrev_b32_e32 v168, 1, v3
	v_mul_i32_i24_e32 v2, 0x700, v3
	v_lshlrev_b32_e32 v3, 2, v165
	s_addc_u32 s69, s73, 0
	v_add3_u32 v199, 0, v2, v3
	v_lshrrev_b32_e32 v2, 2, v163
	s_add_u32 s82, s72, 0x12c00000
	v_writelane_b32 v253, s0, 57
	v_and_b32_e32 v201, 8, v2
	v_lshrrev_b32_e32 v2, 5, v162
	s_addc_u32 s83, s73, 0
	v_ashrrev_i32_e32 v6, 4, v164
	v_lshlrev_b32_e32 v202, 3, v2
	v_lshlrev_b32_e32 v203, 2, v2
	s_add_u32 s84, s72, 0x16c00000
	v_lshrrev_b32_e32 v2, 3, v163
	v_readlane_b32 s0, v253, 1
	v_lshrrev_b32_e32 v5, 4, v162
	v_add_u32_e32 v200, v199, v3
	v_mov_b32_e32 v3, 0
	v_lshrrev_b32_e32 v7, 4, v163
	s_addc_u32 s85, s73, 0
	v_and_b32_e32 v172, 4, v2
	s_lshl_b32 s54, s0, 2
	s_add_i32 s0, 0, 0x1c800
	v_add_u32_e32 v2, 0xfe0, v6
	v_lshl_add_u32 v204, v164, 2, s0
	v_lshlrev_b64 v[174:175], 8, v[2:3]
	v_lshl_add_u32 v205, v163, 2, s0
	v_lshlrev_b32_e32 v176, 8, v7
	v_lshl_or_b32 v2, s86, 2, v5
	s_add_i32 s0, 0, 0x1c000
	v_readlane_b32 s36, v253, 26
	v_subrev_u32_e32 v208, 32, v7
	v_ashrrev_i32_e32 v7, 31, v6
	v_lshl_add_u32 v206, v2, 2, s0
	v_lshlrev_b32_e32 v207, 1, v2
	v_lshlrev_b32_e32 v2, 2, v172
	v_readlane_b32 s40, v253, 30
	v_readlane_b32 s41, v253, 31
	v_lshlrev_b64 v[6:7], 8, v[6:7]
	v_readlane_b32 s1, v253, 2
	v_lshl_add_u64 v[178:179], s[40:41], 0, v[2:3]
	v_or_b32_e32 v6, v6, v1
	v_lshlrev_b32_e32 v2, 4, v163
	v_lshl_add_u64 v[6:7], s[72:73], 0, v[6:7]
	s_mov_b64 s[0:1], 0x1abfe000
	v_lshl_add_u64 v[182:183], s[72:73], 0, v[2:3]
	v_mbcnt_lo_u32_b32 v2, -1, 0
	s_mov_b32 s59, 0
	v_ashrrev_i32_e32 v169, 31, v168
	v_and_b32_e32 v170, 31, v163
	v_cmp_gt_u32_e64 s[20:21], 32, v162
	v_mov_b32_e32 v177, v3
	v_lshl_add_u64 v[180:181], v[6:7], 0, s[0:1]
	v_add_u32_e32 v209, 0x80, v168
	v_lshlrev_b32_e32 v184, 2, v4
	s_mov_b32 s55, 0x200000
	s_mov_b32 s78, 0x3e000000
	s_mov_b32 s79, 0xbfb8aa3b
	s_mov_b32 s56, 0x800000
	s_mov_b32 s57, 0x3f317217
	s_mov_b32 s97, 0x7f800000
	s_mov_b32 s76, 0xc18b3333
	v_mov_b32_e32 v210, 0x358637bd
	v_bfrev_b32_e32 v211, 28
	v_mov_b32_e32 v212, 0x41b17218
	v_mbcnt_hi_u32_b32 v213, -1, v2
	v_mov_b32_e32 v214, 0xf149f2ca
	s_mov_b32 s77, s80
	s_mov_b32 s33, s80
	v_readlane_b32 s37, v253, 27
	v_readlane_b32 s38, v253, 28
	v_readlane_b32 s39, v253, 29
	v_readlane_b32 s42, v253, 32
	v_readlane_b32 s43, v253, 33
	v_readlane_b32 s44, v253, 34
	v_readlane_b32 s45, v253, 35
	v_readlane_b32 s46, v253, 36
	v_readlane_b32 s47, v253, 37
	v_readlane_b32 s48, v253, 38
	v_readlane_b32 s49, v253, 39
	v_readlane_b32 s50, v253, 40
	v_readlane_b32 s51, v253, 41
	s_branch .LBB0_662
